# top-k ranking in the attention unit rewritten branch-free (carry-add counts for both halves)
# speedup vs baseline: 1.0082x; 1.0010x over previous
; __device__ __forceinline__ void attn_unit(int bg, int pb, bool build, const bf16* Q, const bf16* KV, const bf16* KCN, const bf16* VCT, const float* GATES, const float* rel_bias, bf16* A, unsigned char* lds) {
;     ...
;     {
;         const int cur = pb >> 1, pos = tid >> 4;
;         float iv[32];
; #pragma unroll
;         for (int q = 0; q < 8; ++q) { const f32x4 v4 = *(const f32x4*)(impT + pos * 32 + 4 * q); iv[4 * q] = v4.x; iv[4 * q + 1] = v4.y; iv[4 * q + 2] = v4.z; iv[4 * q + 3] = v4.w; }
;         unsigned bits = 0u;
; #pragma unroll
;         for (int h2 = 0; h2 < 2; ++h2) {
;             const int jj = (tid & 15) + 16 * h2;
;             bool sel = false;
;             if (jj <= cur) {
;                 if (jj == 0 || jj == cur || jj == cur - 1) sel = true;
;                 else {
;                     float v = 0.f;
; #pragma unroll
;                     for (int j2 = 0; j2 < 32; ++j2) v = (j2 == jj) ? iv[j2] : v;
;                     int cnt = 3;
; #pragma unroll
;                     for (int j2 = 1; j2 < 30; ++j2) cnt += (j2 <= cur - 2) && (j2 != jj) && ((iv[j2] > v) || (iv[j2] == v && j2 < jj));
;                     sel = cnt < 16;
;                 }
.LBB0_339:
	s_or_b64 exec, exec, s[6:7]
	v_ashrrev_i32_e32 v0, 4, v60
	v_lshl_add_u32 v2, v0, 7, 0
	s_waitcnt lgkmcnt(0)
	s_barrier
	ds_read_b128 v[54:57], v2 offset:34816
	ds_read_b128 v[50:53], v2 offset:34832
	ds_read_b128 v[46:49], v2 offset:34848
	ds_read_b128 v[42:45], v2 offset:34864
	ds_read_b128 v[14:17], v2 offset:34880
	ds_read_b128 v[10:13], v2 offset:34896
	ds_read_b128 v[6:9], v2 offset:34912
	ds_read_b128 v[2:5], v2 offset:34928
	s_lshr_b32 s97, s88, 1
	s_add_i32 s81, s97, -1
	s_waitcnt lgkmcnt(0)
	v_cmp_eq_u32_e64 s[0:1], 0, v58
	v_cmp_eq_u32_e64 s[6:7], 1, v58
	s_nop 0
	v_cndmask_b32_e64 v156, 0, v54, s[0:1]
	v_cndmask_b32_e64 v157, 0, v14, s[0:1]
	v_cmp_eq_u32_e64 s[0:1], 2, v58
	v_cndmask_b32_e64 v156, v156, v55, s[6:7]
	v_cndmask_b32_e64 v157, v157, v15, s[6:7]
	v_cmp_eq_u32_e64 s[6:7], 3, v58
	v_cndmask_b32_e64 v156, v156, v56, s[0:1]
	v_cndmask_b32_e64 v157, v157, v16, s[0:1]
	v_cmp_eq_u32_e64 s[0:1], 4, v58
	v_cndmask_b32_e64 v156, v156, v57, s[6:7]
	v_cndmask_b32_e64 v157, v157, v17, s[6:7]
	v_cmp_eq_u32_e64 s[6:7], 5, v58
	v_cndmask_b32_e64 v156, v156, v50, s[0:1]
	v_cndmask_b32_e64 v157, v157, v10, s[0:1]
	v_cmp_eq_u32_e64 s[0:1], 6, v58
	v_cndmask_b32_e64 v156, v156, v51, s[6:7]
	v_cndmask_b32_e64 v157, v157, v11, s[6:7]
	v_cmp_eq_u32_e64 s[6:7], 7, v58
	v_cndmask_b32_e64 v156, v156, v52, s[0:1]
	v_cndmask_b32_e64 v157, v157, v12, s[0:1]
	v_cmp_eq_u32_e64 s[0:1], 8, v58
	v_cndmask_b32_e64 v156, v156, v53, s[6:7]
	v_cndmask_b32_e64 v157, v157, v13, s[6:7]
	v_cmp_eq_u32_e64 s[6:7], 9, v58
	v_cndmask_b32_e64 v156, v156, v46, s[0:1]
	v_cndmask_b32_e64 v157, v157, v6, s[0:1]
	v_cmp_eq_u32_e64 s[0:1], 10, v58
	v_cndmask_b32_e64 v156, v156, v47, s[6:7]
	v_cndmask_b32_e64 v157, v157, v7, s[6:7]
	v_cmp_eq_u32_e64 s[6:7], 11, v58
	v_cndmask_b32_e64 v156, v156, v48, s[0:1]
	v_cndmask_b32_e64 v157, v157, v8, s[0:1]
	v_cmp_eq_u32_e64 s[0:1], 12, v58
	v_cndmask_b32_e64 v156, v156, v49, s[6:7]
	v_cndmask_b32_e64 v157, v157, v9, s[6:7]
	v_cmp_eq_u32_e64 s[6:7], 13, v58
	v_cndmask_b32_e64 v156, v156, v42, s[0:1]
	v_cndmask_b32_e64 v157, v157, v2, s[0:1]
	v_cmp_eq_u32_e64 s[0:1], 14, v58
	v_cndmask_b32_e64 v156, v156, v43, s[6:7]
	v_cndmask_b32_e64 v157, v157, v3, s[6:7]
	v_cmp_eq_u32_e64 s[6:7], 15, v58
	v_cndmask_b32_e64 v156, v156, v44, s[0:1]
	v_cndmask_b32_e64 v157, v157, v4, s[0:1]
	v_cndmask_b32_e64 v156, v156, v45, s[6:7]
	v_cndmask_b32_e64 v157, v157, v5, s[6:7]
	v_mov_b32_e32 v158, 3
	v_mov_b32_e32 v159, 3
	s_cmp_lt_u32 s97, 3
	s_cbranch_scc1 .Lrk_done
	v_cmp_gt_f32_e64 s[0:1], v55, v156
	v_cmp_ge_f32_e64 s[10:11], v55, v156
	v_cmp_ge_f32_e64 s[6:7], v55, v157
	s_mov_b32 s14, 0xfffcfffc
	s_mov_b32 s15, 0xfffcfffc
	s_and_b64 s[10:11], s[10:11], s[14:15]
	s_or_b64 s[0:1], s[0:1], s[10:11]
	v_addc_co_u32_e64 v158, s[12:13], 0, v158, s[0:1]
	v_addc_co_u32_e64 v159, s[12:13], 0, v159, s[6:7]
	s_cmp_lt_u32 s97, 4
	s_cbranch_scc1 .Lrk_done
	v_cmp_gt_f32_e64 s[0:1], v56, v156
	v_cmp_ge_f32_e64 s[10:11], v56, v156
	v_cmp_ge_f32_e64 s[6:7], v56, v157
	s_mov_b32 s14, 0xfff8fff8
	s_mov_b32 s15, 0xfff8fff8
	s_and_b64 s[10:11], s[10:11], s[14:15]
	s_or_b64 s[0:1], s[0:1], s[10:11]
	v_addc_co_u32_e64 v158, s[12:13], 0, v158, s[0:1]
	v_addc_co_u32_e64 v159, s[12:13], 0, v159, s[6:7]
	s_cmp_lt_u32 s97, 5
	s_cbranch_scc1 .Lrk_done
	v_cmp_gt_f32_e64 s[0:1], v57, v156
	v_cmp_ge_f32_e64 s[10:11], v57, v156
	v_cmp_ge_f32_e64 s[6:7], v57, v157
	s_mov_b32 s14, 0xfff0fff0
	s_mov_b32 s15, 0xfff0fff0
	s_and_b64 s[10:11], s[10:11], s[14:15]
	s_or_b64 s[0:1], s[0:1], s[10:11]
	v_addc_co_u32_e64 v158, s[12:13], 0, v158, s[0:1]
	v_addc_co_u32_e64 v159, s[12:13], 0, v159, s[6:7]
	s_cmp_lt_u32 s97, 6
	s_cbranch_scc1 .Lrk_done
	v_cmp_gt_f32_e64 s[0:1], v50, v156
	v_cmp_ge_f32_e64 s[10:11], v50, v156
	v_cmp_ge_f32_e64 s[6:7], v50, v157
	s_mov_b32 s14, 0xffe0ffe0
	s_mov_b32 s15, 0xffe0ffe0
	s_and_b64 s[10:11], s[10:11], s[14:15]
	s_or_b64 s[0:1], s[0:1], s[10:11]
	v_addc_co_u32_e64 v158, s[12:13], 0, v158, s[0:1]
	v_addc_co_u32_e64 v159, s[12:13], 0, v159, s[6:7]
	s_cmp_lt_u32 s97, 7
	s_cbranch_scc1 .Lrk_done
	v_cmp_gt_f32_e64 s[0:1], v51, v156
	v_cmp_ge_f32_e64 s[10:11], v51, v156
	v_cmp_ge_f32_e64 s[6:7], v51, v157
	s_mov_b32 s14, 0xffc0ffc0
	s_mov_b32 s15, 0xffc0ffc0
	s_and_b64 s[10:11], s[10:11], s[14:15]
	s_or_b64 s[0:1], s[0:1], s[10:11]
	v_addc_co_u32_e64 v158, s[12:13], 0, v158, s[0:1]
	v_addc_co_u32_e64 v159, s[12:13], 0, v159, s[6:7]
	s_cmp_lt_u32 s97, 8
	s_cbranch_scc1 .Lrk_done
	v_cmp_gt_f32_e64 s[0:1], v52, v156
	v_cmp_ge_f32_e64 s[10:11], v52, v156
	v_cmp_ge_f32_e64 s[6:7], v52, v157
	s_mov_b32 s14, 0xff80ff80
	s_mov_b32 s15, 0xff80ff80
	s_and_b64 s[10:11], s[10:11], s[14:15]
	s_or_b64 s[0:1], s[0:1], s[10:11]
	v_addc_co_u32_e64 v158, s[12:13], 0, v158, s[0:1]
	v_addc_co_u32_e64 v159, s[12:13], 0, v159, s[6:7]
	s_cmp_lt_u32 s97, 9
	s_cbranch_scc1 .Lrk_done
	v_cmp_gt_f32_e64 s[0:1], v53, v156
	v_cmp_ge_f32_e64 s[10:11], v53, v156
	v_cmp_ge_f32_e64 s[6:7], v53, v157
	s_mov_b32 s14, 0xff00ff00
	s_mov_b32 s15, 0xff00ff00
	s_and_b64 s[10:11], s[10:11], s[14:15]
	s_or_b64 s[0:1], s[0:1], s[10:11]
	v_addc_co_u32_e64 v158, s[12:13], 0, v158, s[0:1]
	v_addc_co_u32_e64 v159, s[12:13], 0, v159, s[6:7]
	s_cmp_lt_u32 s97, 10
	s_cbranch_scc1 .Lrk_done
	v_cmp_gt_f32_e64 s[0:1], v46, v156
	v_cmp_ge_f32_e64 s[10:11], v46, v156
	v_cmp_ge_f32_e64 s[6:7], v46, v157
	s_mov_b32 s14, 0xfe00fe00
	s_mov_b32 s15, 0xfe00fe00
	s_and_b64 s[10:11], s[10:11], s[14:15]
	s_or_b64 s[0:1], s[0:1], s[10:11]
	v_addc_co_u32_e64 v158, s[12:13], 0, v158, s[0:1]
	v_addc_co_u32_e64 v159, s[12:13], 0, v159, s[6:7]
	s_cmp_lt_u32 s97, 11
	s_cbranch_scc1 .Lrk_done
; __device__ __forceinline__ void attn_unit(int bg, int pb, bool build, const bf16* Q, const bf16* KV, const bf16* KCN, const bf16* VCT, const float* GATES, const float* rel_bias, bf16* A, unsigned char* lds) {
;     ...
;                     float v = 0.f;
; #pragma unroll
;                     for (int j2 = 0; j2 < 32; ++j2) v = (j2 == jj) ? iv[j2] : v;
;                     int cnt = 3;
; #pragma unroll
;                     for (int j2 = 1; j2 < 30; ++j2) cnt += (j2 <= cur - 2) && (j2 != jj) && ((iv[j2] > v) || (iv[j2] == v && j2 < jj));
;                     sel = cnt < 16;
;                 }
	v_cmp_gt_f32_e64 s[0:1], v47, v156
	v_cmp_ge_f32_e64 s[10:11], v47, v156
	v_cmp_ge_f32_e64 s[6:7], v47, v157
	s_mov_b32 s14, 0xfc00fc00
	s_mov_b32 s15, 0xfc00fc00
	s_and_b64 s[10:11], s[10:11], s[14:15]
	s_or_b64 s[0:1], s[0:1], s[10:11]
	v_addc_co_u32_e64 v158, s[12:13], 0, v158, s[0:1]
	v_addc_co_u32_e64 v159, s[12:13], 0, v159, s[6:7]
	s_cmp_lt_u32 s97, 12
	s_cbranch_scc1 .Lrk_done
	v_cmp_gt_f32_e64 s[0:1], v48, v156
	v_cmp_ge_f32_e64 s[10:11], v48, v156
	v_cmp_ge_f32_e64 s[6:7], v48, v157
	s_mov_b32 s14, 0xf800f800
	s_mov_b32 s15, 0xf800f800
	s_and_b64 s[10:11], s[10:11], s[14:15]
	s_or_b64 s[0:1], s[0:1], s[10:11]
	v_addc_co_u32_e64 v158, s[12:13], 0, v158, s[0:1]
	v_addc_co_u32_e64 v159, s[12:13], 0, v159, s[6:7]
	s_cmp_lt_u32 s97, 13
	s_cbranch_scc1 .Lrk_done
	v_cmp_gt_f32_e64 s[0:1], v49, v156
	v_cmp_ge_f32_e64 s[10:11], v49, v156
	v_cmp_ge_f32_e64 s[6:7], v49, v157
	s_mov_b32 s14, 0xf000f000
	s_mov_b32 s15, 0xf000f000
	s_and_b64 s[10:11], s[10:11], s[14:15]
	s_or_b64 s[0:1], s[0:1], s[10:11]
	v_addc_co_u32_e64 v158, s[12:13], 0, v158, s[0:1]
	v_addc_co_u32_e64 v159, s[12:13], 0, v159, s[6:7]
	s_cmp_lt_u32 s97, 14
	s_cbranch_scc1 .Lrk_done
	v_cmp_gt_f32_e64 s[0:1], v42, v156
	v_cmp_ge_f32_e64 s[10:11], v42, v156
	v_cmp_ge_f32_e64 s[6:7], v42, v157
	s_mov_b32 s14, 0xe000e000
	s_mov_b32 s15, 0xe000e000
	s_and_b64 s[10:11], s[10:11], s[14:15]
	s_or_b64 s[0:1], s[0:1], s[10:11]
	v_addc_co_u32_e64 v158, s[12:13], 0, v158, s[0:1]
	v_addc_co_u32_e64 v159, s[12:13], 0, v159, s[6:7]
	s_cmp_lt_u32 s97, 15
	s_cbranch_scc1 .Lrk_done
	v_cmp_gt_f32_e64 s[0:1], v43, v156
	v_cmp_ge_f32_e64 s[10:11], v43, v156
	v_cmp_ge_f32_e64 s[6:7], v43, v157
	s_mov_b32 s14, 0xc000c000
	s_mov_b32 s15, 0xc000c000
	s_and_b64 s[10:11], s[10:11], s[14:15]
	s_or_b64 s[0:1], s[0:1], s[10:11]
	v_addc_co_u32_e64 v158, s[12:13], 0, v158, s[0:1]
	v_addc_co_u32_e64 v159, s[12:13], 0, v159, s[6:7]
	s_cmp_lt_u32 s97, 16
	s_cbranch_scc1 .Lrk_done
	v_cmp_gt_f32_e64 s[0:1], v44, v156
	v_cmp_ge_f32_e64 s[10:11], v44, v156
	v_cmp_ge_f32_e64 s[6:7], v44, v157
	s_mov_b32 s14, 0x80008000
	s_mov_b32 s15, 0x80008000
	s_and_b64 s[10:11], s[10:11], s[14:15]
	s_or_b64 s[0:1], s[0:1], s[10:11]
	v_addc_co_u32_e64 v158, s[12:13], 0, v158, s[0:1]
	v_addc_co_u32_e64 v159, s[12:13], 0, v159, s[6:7]
	s_cmp_lt_u32 s97, 17
	s_cbranch_scc1 .Lrk_done
	v_cmp_gt_f32_e64 s[0:1], v45, v156
	v_cmp_ge_f32_e64 s[6:7], v45, v157
	s_nop 0
	v_addc_co_u32_e64 v158, s[12:13], 0, v158, s[0:1]
	v_addc_co_u32_e64 v159, s[12:13], 0, v159, s[6:7]
	s_cmp_lt_u32 s97, 18
	s_cbranch_scc1 .Lrk_done
	v_cmp_gt_f32_e64 s[0:1], v14, v156
	v_cmp_gt_f32_e64 s[6:7], v14, v157
	v_cmp_ge_f32_e64 s[10:11], v14, v157
	s_mov_b32 s14, 0xfffefffe
	s_mov_b32 s15, 0xfffefffe
	s_and_b64 s[10:11], s[10:11], s[14:15]
	s_or_b64 s[6:7], s[6:7], s[10:11]
	v_addc_co_u32_e64 v158, s[12:13], 0, v158, s[0:1]
	v_addc_co_u32_e64 v159, s[12:13], 0, v159, s[6:7]
	s_cmp_lt_u32 s97, 19
	s_cbranch_scc1 .Lrk_done
	v_cmp_gt_f32_e64 s[0:1], v15, v156
	v_cmp_gt_f32_e64 s[6:7], v15, v157
	v_cmp_ge_f32_e64 s[10:11], v15, v157
	s_mov_b32 s14, 0xfffcfffc
	s_mov_b32 s15, 0xfffcfffc
	s_and_b64 s[10:11], s[10:11], s[14:15]
	s_or_b64 s[6:7], s[6:7], s[10:11]
	v_addc_co_u32_e64 v158, s[12:13], 0, v158, s[0:1]
	v_addc_co_u32_e64 v159, s[12:13], 0, v159, s[6:7]
	s_cmp_lt_u32 s97, 20
	s_cbranch_scc1 .Lrk_done
	v_cmp_gt_f32_e64 s[0:1], v16, v156
	v_cmp_gt_f32_e64 s[6:7], v16, v157
	v_cmp_ge_f32_e64 s[10:11], v16, v157
	s_mov_b32 s14, 0xfff8fff8
	s_mov_b32 s15, 0xfff8fff8
	s_and_b64 s[10:11], s[10:11], s[14:15]
	s_or_b64 s[6:7], s[6:7], s[10:11]
	v_addc_co_u32_e64 v158, s[12:13], 0, v158, s[0:1]
	v_addc_co_u32_e64 v159, s[12:13], 0, v159, s[6:7]
	s_cmp_lt_u32 s97, 21
	s_cbranch_scc1 .Lrk_done
	v_cmp_gt_f32_e64 s[0:1], v17, v156
	v_cmp_gt_f32_e64 s[6:7], v17, v157
	v_cmp_ge_f32_e64 s[10:11], v17, v157
	s_mov_b32 s14, 0xfff0fff0
	s_mov_b32 s15, 0xfff0fff0
	s_and_b64 s[10:11], s[10:11], s[14:15]
	s_or_b64 s[6:7], s[6:7], s[10:11]
	v_addc_co_u32_e64 v158, s[12:13], 0, v158, s[0:1]
	v_addc_co_u32_e64 v159, s[12:13], 0, v159, s[6:7]
	s_cmp_lt_u32 s97, 22
	s_cbranch_scc1 .Lrk_done
	v_cmp_gt_f32_e64 s[0:1], v10, v156
	v_cmp_gt_f32_e64 s[6:7], v10, v157
	v_cmp_ge_f32_e64 s[10:11], v10, v157
	s_mov_b32 s14, 0xffe0ffe0
	s_mov_b32 s15, 0xffe0ffe0
	s_and_b64 s[10:11], s[10:11], s[14:15]
	s_or_b64 s[6:7], s[6:7], s[10:11]
	v_addc_co_u32_e64 v158, s[12:13], 0, v158, s[0:1]
	v_addc_co_u32_e64 v159, s[12:13], 0, v159, s[6:7]
	s_cmp_lt_u32 s97, 23
	s_cbranch_scc1 .Lrk_done
	v_cmp_gt_f32_e64 s[0:1], v11, v156
	v_cmp_gt_f32_e64 s[6:7], v11, v157
	v_cmp_ge_f32_e64 s[10:11], v11, v157
	s_mov_b32 s14, 0xffc0ffc0
	s_mov_b32 s15, 0xffc0ffc0
	s_and_b64 s[10:11], s[10:11], s[14:15]
	s_or_b64 s[6:7], s[6:7], s[10:11]
	v_addc_co_u32_e64 v158, s[12:13], 0, v158, s[0:1]
	v_addc_co_u32_e64 v159, s[12:13], 0, v159, s[6:7]
	s_cmp_lt_u32 s97, 24
	s_cbranch_scc1 .Lrk_done
; #define AT_LOAD(s_, k_, v_) do { k_ = *(const u32x4*)(kg + (size_t)(s_) * 4096); v_ = *(const u32x4*)(vg + (s_) * 64); } while (0)
; template <int MODE> ...
;     ...
;     const int crow = tid >> 3, cch = tid & 7;
;     const bf16* kg = K + (size_t)crow * 64 + cch * 8;
;     const bf16* vg = VT + (size_t)crow * 2048 + cch * 8;
;     const int kdst = crow * AKP + cch * 16;
;     const int vdst = 9216 + crow * AKP + ((cch >> 2) * 32 + (cch & 1) * 16 + ((cch & 3) >> 1) * 4) * 2;
;     const int koff = qi * AKP + q4 * 16, voff = 9216 + qi * AKP + q4 * 16;
;     unsigned char* sb0 = lds + AL_KV0; unsigned char* sb1 = sb0 + KV_STAGE;
;     ...
;     u32x4 ka, va, kb = {0u, 0u, 0u, 0u}, vb = {0u, 0u, 0u, 0u};
;     AT_LOAD(st_lo, ka, va);
;     if (st_lo + 1 <= st_hi) AT_LOAD(st_lo + 1, kb, vb);
; __device__ __forceinline__ void attn_unit(int bg, int pb, bool build, const bf16* Q, const bf16* KV, const bf16* KCN, const bf16* VCT, const float* GATES, const float* rel_bias, bf16* A, unsigned char* lds) {
;     ...
;                     float v = 0.f;
; #pragma unroll
;                     for (int j2 = 0; j2 < 32; ++j2) v = (j2 == jj) ? iv[j2] : v;
;                     int cnt = 3;
; #pragma unroll
;                     for (int j2 = 1; j2 < 30; ++j2) cnt += (j2 <= cur - 2) && (j2 != jj) && ((iv[j2] > v) || (iv[j2] == v && j2 < jj));
;                     sel = cnt < 16;
;                 }
;             }
;             if (sel) bits |= 1u << jj;
;         }
;         if (bits) atomicOr(&selw[pos], bits);
;     }
;     __syncthreads();
;     const unsigned selm = selw[half * 16 + qi];
	v_cmp_gt_f32_e64 s[0:1], v12, v156
	v_cmp_gt_f32_e64 s[6:7], v12, v157
	v_cmp_ge_f32_e64 s[10:11], v12, v157
	s_mov_b32 s14, 0xff80ff80
	s_mov_b32 s15, 0xff80ff80
	s_and_b64 s[10:11], s[10:11], s[14:15]
	s_or_b64 s[6:7], s[6:7], s[10:11]
	v_addc_co_u32_e64 v158, s[12:13], 0, v158, s[0:1]
	v_addc_co_u32_e64 v159, s[12:13], 0, v159, s[6:7]
	s_cmp_lt_u32 s97, 25
	s_cbranch_scc1 .Lrk_done
	v_cmp_gt_f32_e64 s[0:1], v13, v156
	v_cmp_gt_f32_e64 s[6:7], v13, v157
	v_cmp_ge_f32_e64 s[10:11], v13, v157
	s_mov_b32 s14, 0xff00ff00
	s_mov_b32 s15, 0xff00ff00
	s_and_b64 s[10:11], s[10:11], s[14:15]
	s_or_b64 s[6:7], s[6:7], s[10:11]
	v_addc_co_u32_e64 v158, s[12:13], 0, v158, s[0:1]
	v_addc_co_u32_e64 v159, s[12:13], 0, v159, s[6:7]
	s_cmp_lt_u32 s97, 26
	s_cbranch_scc1 .Lrk_done
	v_cmp_gt_f32_e64 s[0:1], v6, v156
	v_cmp_gt_f32_e64 s[6:7], v6, v157
	v_cmp_ge_f32_e64 s[10:11], v6, v157
	s_mov_b32 s14, 0xfe00fe00
	s_mov_b32 s15, 0xfe00fe00
	s_and_b64 s[10:11], s[10:11], s[14:15]
	s_or_b64 s[6:7], s[6:7], s[10:11]
	v_addc_co_u32_e64 v158, s[12:13], 0, v158, s[0:1]
	v_addc_co_u32_e64 v159, s[12:13], 0, v159, s[6:7]
	s_cmp_lt_u32 s97, 27
	s_cbranch_scc1 .Lrk_done
	v_cmp_gt_f32_e64 s[0:1], v7, v156
	v_cmp_gt_f32_e64 s[6:7], v7, v157
	v_cmp_ge_f32_e64 s[10:11], v7, v157
	s_mov_b32 s14, 0xfc00fc00
	s_mov_b32 s15, 0xfc00fc00
	s_and_b64 s[10:11], s[10:11], s[14:15]
	s_or_b64 s[6:7], s[6:7], s[10:11]
	v_addc_co_u32_e64 v158, s[12:13], 0, v158, s[0:1]
	v_addc_co_u32_e64 v159, s[12:13], 0, v159, s[6:7]
	s_cmp_lt_u32 s97, 28
	s_cbranch_scc1 .Lrk_done
	v_cmp_gt_f32_e64 s[0:1], v8, v156
	v_cmp_gt_f32_e64 s[6:7], v8, v157
	v_cmp_ge_f32_e64 s[10:11], v8, v157
	s_mov_b32 s14, 0xf800f800
	s_mov_b32 s15, 0xf800f800
	s_and_b64 s[10:11], s[10:11], s[14:15]
	s_or_b64 s[6:7], s[6:7], s[10:11]
	v_addc_co_u32_e64 v158, s[12:13], 0, v158, s[0:1]
	v_addc_co_u32_e64 v159, s[12:13], 0, v159, s[6:7]
	s_cmp_lt_u32 s97, 29
	s_cbranch_scc1 .Lrk_done
	v_cmp_gt_f32_e64 s[0:1], v9, v156
	v_cmp_gt_f32_e64 s[6:7], v9, v157
	v_cmp_ge_f32_e64 s[10:11], v9, v157
	s_mov_b32 s14, 0xf000f000
	s_mov_b32 s15, 0xf000f000
	s_and_b64 s[10:11], s[10:11], s[14:15]
	s_or_b64 s[6:7], s[6:7], s[10:11]
	v_addc_co_u32_e64 v158, s[12:13], 0, v158, s[0:1]
	v_addc_co_u32_e64 v159, s[12:13], 0, v159, s[6:7]
	s_cmp_lt_u32 s97, 30
	s_cbranch_scc1 .Lrk_done
	v_cmp_gt_f32_e64 s[0:1], v2, v156
	v_cmp_gt_f32_e64 s[6:7], v2, v157
	v_cmp_ge_f32_e64 s[10:11], v2, v157
	s_mov_b32 s14, 0xe000e000
	s_mov_b32 s15, 0xe000e000
	s_and_b64 s[10:11], s[10:11], s[14:15]
	s_or_b64 s[6:7], s[6:7], s[10:11]
	v_addc_co_u32_e64 v158, s[12:13], 0, v158, s[0:1]
	v_addc_co_u32_e64 v159, s[12:13], 0, v159, s[6:7]
	s_cmp_lt_u32 s97, 31
	s_cbranch_scc1 .Lrk_done
	v_cmp_gt_f32_e64 s[0:1], v3, v156
	v_cmp_gt_f32_e64 s[6:7], v3, v157
	v_cmp_ge_f32_e64 s[10:11], v3, v157
	s_mov_b32 s14, 0xc000c000
	s_mov_b32 s15, 0xc000c000
	s_and_b64 s[10:11], s[10:11], s[14:15]
	s_or_b64 s[6:7], s[6:7], s[10:11]
	v_addc_co_u32_e64 v158, s[12:13], 0, v158, s[0:1]
	v_addc_co_u32_e64 v159, s[12:13], 0, v159, s[6:7]
.Lrk_done:
	v_add_u32_e32 v161, 16, v58
	v_cmp_gt_u32_e64 s[0:1], 16, v158
	v_cmp_eq_u32_e64 s[6:7], 0, v58
	v_cmp_eq_u32_e64 s[10:11], s97, v58
	v_cmp_eq_u32_e64 s[12:13], s81, v58
	v_cmp_ge_u32_e64 s[14:15], s97, v58
	s_or_b64 s[0:1], s[0:1], s[6:7]
	s_or_b64 s[0:1], s[0:1], s[10:11]
	s_or_b64 s[0:1], s[0:1], s[12:13]
	s_and_b64 s[0:1], s[0:1], s[14:15]
	v_cndmask_b32_e64 v160, 0, 1, s[0:1]
	v_cmp_gt_u32_e64 s[0:1], 16, v159
	v_cmp_eq_u32_e64 s[10:11], s97, v161
	v_cmp_eq_u32_e64 s[12:13], s81, v161
	v_cmp_ge_u32_e64 s[14:15], s97, v161
	v_lshlrev_b32_e32 v54, v58, v160
	s_or_b64 s[0:1], s[0:1], s[10:11]
	s_or_b64 s[0:1], s[0:1], s[12:13]
	s_and_b64 s[0:1], s[0:1], s[14:15]
	v_cndmask_b32_e64 v160, 0, 1, s[0:1]
	v_lshlrev_b32_e32 v160, v161, v160
	v_or_b32_e32 v54, v54, v160
	v_cmp_ne_u32_e32 vcc, 0, v54
	s_and_saveexec_b64 s[0:1], vcc
	v_lshl_add_u32 v0, v0, 2, 0
	ds_or_b32 v0, v54 offset:38912
	s_or_b64 exec, exec, s[0:1]
	s_lshl_b32 s0, s75, 2
	s_add_i32 s0, s0, 0
	v_lshl_add_u32 v0, v58, 2, s0
	s_lshl_b32 s6, s69, 18
	v_readlane_b32 s0, v255, 42
	s_add_u32 s0, s0, s6
	v_readlane_b32 s1, v255, 43
	s_waitcnt lgkmcnt(4)
	v_ashrrev_i32_e32 v42, 3, v60
	s_addc_u32 s1, s1, 0
	v_readlane_b32 s7, v255, 45
	v_ashrrev_i32_e32 v43, 31, v42
	s_add_u32 s6, s7, s6
	v_readlane_b32 s7, v255, 46
	v_and_b32_e32 v44, 7, v60
	v_lshlrev_b64 v[106:107], 7, v[42:43]
	s_waitcnt lgkmcnt(0)
	s_barrier
	ds_read_b32 v115, v0 offset:38912
	s_addc_u32 s7, s7, 0
	v_lshl_add_u64 v[2:3], s[0:1], 0, v[106:107]
	v_lshlrev_b32_e32 v0, 4, v44
	v_lshlrev_b64 v[108:109], 12, v[42:43]
	v_lshl_add_u64 v[10:11], v[2:3], 0, v[0:1]
	v_lshl_add_u64 v[2:3], s[6:7], 0, v[108:109]
	v_lshl_add_u64 v[14:15], v[2:3], 0, v[0:1]
	global_load_dwordx4 v[2:5], v[10:11], off
	global_load_dwordx4 v[6:9], v[14:15], off
	s_cmp_lt_u32 s88, 2
	s_cbranch_scc1 .LBB0_587
	v_add_co_u32_e32 v10, vcc, 0x2000, v10
	s_nop 1
	v_addc_co_u32_e32 v11, vcc, 0, v11, vcc
	global_load_dwordx4 v[10:13], v[10:11], off
	s_nop 0
	global_load_dwordx4 v[14:17], v[14:15], off offset:128
	s_branch .LBB0_588
